# cscan: pair the two v-halves of each chain on workgroups bid/bid+8 (same XCD L2)
# speedup vs baseline: 1.0060x; 1.0060x over previous
.LBB0_977:
	s_cmpk_gt_i32 s5, 0xff
	s_cselect_b64 s[6:7], -1, 0
	s_add_i32 s10, s5, 0xffffff00
	s_cmpk_lt_i32 s5, 0x100
	s_cselect_b64 s[8:9], -1, 0
	s_and_b64 vcc, s[8:9], exec
	v_writelane_b32 v255, s6, 57
	s_cselect_b32 s11, s5, s10
	s_and_b32 s100, s11, 7
	s_lshl_b32 s100, s100, 1
	s_bfe_u32 s101, s11, 0x10003
	s_or_b32 s100, s100, s101
	s_andn2_b32 s11, s11, 15
	s_or_b32 s11, s11, s100
	s_bfe_u32 s16, s11, 0x10005
	v_writelane_b32 v255, s7, 58
	s_cbranch_vccnz .LBB0_979
	s_mov_b64 s[14:15], 0
	s_branch .LBB0_980

	.amdhsa_kernel _Z4mega4Args
		.amdhsa_group_segment_fixed_size 0
		.amdhsa_private_segment_fixed_size 0
		.amdhsa_kernarg_size 648
		.amdhsa_user_sgpr_count 2
		.amdhsa_user_sgpr_dispatch_ptr 0
		.amdhsa_user_sgpr_queue_ptr 0
		.amdhsa_user_sgpr_kernarg_segment_ptr 1
		.amdhsa_user_sgpr_dispatch_id 0
		.amdhsa_user_sgpr_kernarg_preload_length 0
		.amdhsa_user_sgpr_kernarg_preload_offset 0
		.amdhsa_user_sgpr_private_segment_size 0
		.amdhsa_uses_dynamic_stack 0
		.amdhsa_enable_private_segment 0
		.amdhsa_system_sgpr_workgroup_id_x 1
		.amdhsa_system_sgpr_workgroup_id_y 0
		.amdhsa_system_sgpr_workgroup_id_z 0
		.amdhsa_system_sgpr_workgroup_info 0
		.amdhsa_system_vgpr_workitem_id 0
		.amdhsa_next_free_vgpr 256
		.amdhsa_next_free_sgpr 102
		.amdhsa_accum_offset 256
		.amdhsa_reserve_vcc 1
		.amdhsa_float_round_mode_32 0
		.amdhsa_float_round_mode_16_64 0
		.amdhsa_float_denorm_mode_32 3
		.amdhsa_float_denorm_mode_16_64 3
		.amdhsa_dx10_clamp 1
		.amdhsa_ieee_mode 1
		.amdhsa_fp16_overflow 0
		.amdhsa_tg_split 0
		.amdhsa_exception_fp_ieee_invalid_op 0
		.amdhsa_exception_fp_denorm_src 0
		.amdhsa_exception_fp_ieee_div_zero 0
		.amdhsa_exception_fp_ieee_overflow 0
		.amdhsa_exception_fp_ieee_underflow 0
		.amdhsa_exception_fp_ieee_inexact 0
		.amdhsa_exception_int_div_zero 0
	.end_amdhsa_kernel

amdhsa.kernels:
  - .agpr_count:     0
    .args:
      - .offset:         0
        .size:           392
        .value_kind:     by_value
      - .offset:         392
        .size:           4
        .value_kind:     hidden_block_count_x
      - .offset:         396
        .size:           4
        .value_kind:     hidden_block_count_y
      - .offset:         400
        .size:           4
        .value_kind:     hidden_block_count_z
      - .offset:         404
        .size:           2
        .value_kind:     hidden_group_size_x
      - .offset:         406
        .size:           2
        .value_kind:     hidden_group_size_y
      - .offset:         408
        .size:           2
        .value_kind:     hidden_group_size_z
      - .offset:         410
        .size:           2
        .value_kind:     hidden_remainder_x
      - .offset:         412
        .size:           2
        .value_kind:     hidden_remainder_y
      - .offset:         414
        .size:           2
        .value_kind:     hidden_remainder_z
      - .offset:         432
        .size:           8
        .value_kind:     hidden_global_offset_x
      - .offset:         440
        .size:           8
        .value_kind:     hidden_global_offset_y
      - .offset:         448
        .size:           8
        .value_kind:     hidden_global_offset_z
      - .offset:         456
        .size:           2
        .value_kind:     hidden_grid_dims
      - .offset:         512
        .size:           4
        .value_kind:     hidden_dynamic_lds_size
    .group_segment_fixed_size: 0
    .kernarg_segment_align: 8
    .kernarg_segment_size: 648
    .language:       OpenCL C
    .language_version:
      - 2
      - 0
    .max_flat_workgroup_size: 512
    .name:           _Z4mega4Args
    .private_segment_fixed_size: 0
    .sgpr_count:     108
    .sgpr_spill_count: 254
    .symbol:         _Z4mega4Args.kd
    .uniform_work_group_size: 1
    .uses_dynamic_stack: false
    .vgpr_count:     256
    .vgpr_spill_count: 0
    .wavefront_size: 64
